# LN1 and LN2 row loops: gamma/beta hoisted out of loop, next-row prefetch with counted vmcnt
# baseline (speedup 1.0000x reference)
; DI float bflo(unsigned u) { return __uint_as_float(u << 16); }
; DI float bfhi(unsigned u) { return __uint_as_float(u & 0xffff0000u); }
; template <bool TO_BF16>
; DI void phase_ln(const Params& P, const float* gam, const float* bet) {
;   const int wid = threadIdx.x >> 6, lane = threadIdx.x & 63;
;   float* Y = P.out + O_Y;
;   u16* X1 = (u16*)(P.ws + R_X1);
;   const u16* SRC = (const u16*)(P.ws + (TO_BF16 ? R_TB : R_T2B));
;   for (long row = (long)blockIdx.x * 8 + wid; row < MTOK; row += (long)gridDim.x * 8) {
;     const u16* src = SRC + row * 1024;
;     float v[16];
;     float s = 0.f;
;     for (int k = 0; k < 2; ++k) {
;       const u32x4_ u_ = __builtin_nontemporal_load((const u32x4_*)(src + k * 512 + lane * 8));
;       const uint4 u = make_uint4(u_[0], u_[1], u_[2], u_[3]);
;       v[8 * k + 0] = bflo(u.x); v[8 * k + 1] = bfhi(u.x); v[8 * k + 2] = bflo(u.y); v[8 * k + 3] = bfhi(u.y);
;       v[8 * k + 4] = bflo(u.z); v[8 * k + 5] = bfhi(u.z); v[8 * k + 6] = bflo(u.w); v[8 * k + 7] = bfhi(u.w);
;     }
;     for (int e = 0; e < 16; ++e) s += v[e];
;     for (int d = 1; d < 64; d <<= 1) s += __shfl_xor(s, d);
;     const float mean = s * (1.0f / 1024.0f);
;     float s2 = 0.f;
;     for (int e = 0; e < 16; ++e) { const float d = v[e] - mean; s2 += d * d; }
;     for (int d = 1; d < 64; d <<= 1) s2 += __shfl_xor(s2, d);
;     const float rstd = rsqrtf(s2 * (1.0f / 1024.0f) + 1e-5f);
;     for (int k = 0; k < 2; ++k) {
;       const int c = k * 512 + lane * 8;
;       f32x4 g0 = *(const f32x4*)(gam + c), g1 = *(const f32x4*)(gam + c + 4), b0 = *(const f32x4*)(bet + c), b1 = *(const f32x4*)(bet + c + 4), r0, r1;
.LBB0_927:
	s_cmp_lt_i32 s96, 6
	s_cselect_b64 s[0:1], -1, 0
	s_cmp_gt_i32 s97, 5
	s_cselect_b64 s[2:3], -1, 0
	s_and_b64 s[0:1], s[0:1], s[2:3]
	s_andn2_b64 vcc, exec, s[0:1]
	v_bfe_u32 v1, v0, 6, 4
	s_cbranch_vccnz .LBB0_943
	v_readlane_b32 s0, v250, 2
	v_readlane_b32 s1, v250, 3
	s_load_dwordx4 s[4:7], s[0:1], 0xa8
	s_mov_b32 s91, 0
	s_lshl_b64 s[0:1], s[90:91], 3
	v_or_b32_e32 v2, s0, v1
	v_mov_b32_e32 v3, s1
	s_mov_b64 s[0:1], 0x10100
	v_and_b32_e32 v10, 0x3ff, v0
	s_waitcnt lgkmcnt(0)
	s_mov_b64 s[2:3], s[4:5]
	v_cmp_gt_u64_e32 vcc, s[0:1], v[2:3]
	s_and_saveexec_b64 s[0:1], vcc
	s_cbranch_execz .LBB0_931
	v_mbcnt_lo_u32_b32 v4, -1, 0
	v_mbcnt_hi_u32_b32 v4, -1, v4
	v_and_b32_e32 v5, 64, v4
	v_add_u32_e32 v5, 64, v5
	v_xor_b32_e32 v6, 1, v4
	v_cmp_lt_i32_e32 vcc, v6, v5
	v_readlane_b32 s2, v250, 2
	v_readlane_b32 s3, v250, 3
	v_cndmask_b32_e32 v6, v4, v6, vcc
	v_lshlrev_b32_e32 v11, 2, v6
	v_xor_b32_e32 v6, 2, v4
	v_cmp_lt_i32_e32 vcc, v6, v5
	s_load_dwordx4 s[8:11], s[2:3], 0x70
	v_mov_b32_e32 v9, 0
	v_cndmask_b32_e32 v6, v4, v6, vcc
	v_lshlrev_b32_e32 v12, 2, v6
	v_xor_b32_e32 v6, 4, v4
	v_cmp_lt_i32_e32 vcc, v6, v5
	s_lshl_b64 s[4:5], s[90:91], 14
	v_and_b32_e32 v17, 63, v10
	v_cndmask_b32_e32 v6, v4, v6, vcc
	v_lshlrev_b32_e32 v13, 2, v6
	v_xor_b32_e32 v6, 8, v4
	v_cmp_lt_i32_e32 vcc, v6, v5
	v_readlane_b32 s2, v250, 0
	s_mov_b32 s12, s2
	v_cndmask_b32_e32 v6, v4, v6, vcc
	v_lshlrev_b32_e32 v14, 2, v6
	v_xor_b32_e32 v6, 16, v4
	v_cmp_lt_i32_e32 vcc, v6, v5
	v_readlane_b32 s3, v250, 1
	s_mov_b32 s13, s91
	v_cndmask_b32_e32 v6, v4, v6, vcc
	v_lshlrev_b32_e32 v15, 2, v6
	v_xor_b32_e32 v6, 32, v4
	v_cmp_lt_i32_e32 vcc, v6, v5
	s_lshl_b64 s[2:3], s[12:13], 3
	s_nop 0
	v_cndmask_b32_e32 v4, v4, v6, vcc
	v_lshlrev_b32_e32 v16, 2, v4
	v_lshlrev_b32_e32 v4, 5, v10
	v_and_b32_e32 v8, 0x7e0, v4
	s_waitcnt lgkmcnt(0)
	v_lshl_add_u64 v[4:5], s[8:9], 0, v[8:9]
	v_lshl_add_u64 v[6:7], s[10:11], 0, v[8:9]
	v_lshlrev_b32_e32 v8, 11, v1
	v_lshl_add_u64 v[8:9], s[4:5], 0, v[8:9]
	v_lshl_or_b32 v8, v17, 4, v8
	v_lshl_add_u64 v[8:9], s[6:7], 0, v[8:9]
	s_mov_b64 s[4:5], 0x2f57b900
	v_lshl_add_u64 v[8:9], v[8:9], 0, s[4:5]
	s_mov_b32 s4, s12
	v_writelane_b32 v250, s4, 0
	s_mov_b64 s[6:7], 0
	v_mov_b32_e32 v17, 0x3727c5ac
	v_writelane_b32 v250, s5, 1
	s_lshl_b64 s[4:5], s[12:13], 14
	s_mov_b32 s10, 0x800000
	s_mov_b64 s[8:9], 0x100ff
	global_load_dwordx4 v[74:77], v[4:5], off
	global_load_dwordx4 v[78:81], v[4:5], off offset:16
	global_load_dwordx4 v[82:85], v[6:7], off
	global_load_dwordx4 v[86:89], v[6:7], off offset:16
	global_load_dwordx4 v[90:93], v[4:5], off offset:2048
	global_load_dwordx4 v[94:97], v[4:5], off offset:2064
	global_load_dwordx4 v[98:101], v[6:7], off offset:2048
	global_load_dwordx4 v[102:105], v[6:7], off offset:2064
	v_add_co_u32_e32 v70, vcc, 0xd704f000, v8
	s_nop 1
	v_addc_co_u32_e32 v71, vcc, -1, v9, vcc
	global_load_dwordx4 v[18:21], v[70:71], off nt
	global_load_dwordx4 v[22:25], v[70:71], off offset:1024 nt
	s_waitcnt vmcnt(0)
; DI float bflo(unsigned u) { return __uint_as_float(u << 16); }
; DI float bfhi(unsigned u) { return __uint_as_float(u & 0xffff0000u); }
; DI uint4 pk8(f32x4 a, f32x4 b) { return make_uint4(pack2(a[0], a[1]), pack2(a[2], a[3]), pack2(b[0], b[1]), pack2(b[2], b[3])); }
; template <bool TO_BF16>
; DI void phase_ln(const Params& P, const float* gam, const float* bet) {
;     ...
;   for (long row = (long)blockIdx.x * 8 + wid; row < MTOK; row += (long)gridDim.x * 8) {
;     const u16* src = SRC + row * 1024;
;     float v[16];
;     float s = 0.f;
;     for (int k = 0; k < 2; ++k) {
;       const u32x4_ u_ = __builtin_nontemporal_load((const u32x4_*)(src + k * 512 + lane * 8));
;       const uint4 u = make_uint4(u_[0], u_[1], u_[2], u_[3]);
;       v[8 * k + 0] = bflo(u.x); v[8 * k + 1] = bfhi(u.x); v[8 * k + 2] = bflo(u.y); v[8 * k + 3] = bfhi(u.y);
;       v[8 * k + 4] = bflo(u.z); v[8 * k + 5] = bfhi(u.z); v[8 * k + 6] = bflo(u.w); v[8 * k + 7] = bfhi(u.w);
;     }
;     for (int e = 0; e < 16; ++e) s += v[e];
;     for (int d = 1; d < 64; d <<= 1) s += __shfl_xor(s, d);
;     const float mean = s * (1.0f / 1024.0f);
;     float s2 = 0.f;
;     for (int e = 0; e < 16; ++e) { const float d = v[e] - mean; s2 += d * d; }
;     for (int d = 1; d < 64; d <<= 1) s2 += __shfl_xor(s2, d);
;     const float rstd = rsqrtf(s2 * (1.0f / 1024.0f) + 1e-5f);
;     for (int k = 0; k < 2; ++k) {
;       const int c = k * 512 + lane * 8;
;       f32x4 g0 = *(const f32x4*)(gam + c), g1 = *(const f32x4*)(gam + c + 4), b0 = *(const f32x4*)(bet + c), b1 = *(const f32x4*)(bet + c + 4), r0, r1;
;       for (int j = 0; j < 4; ++j) { r0[j] = (v[8 * k + j] - mean) * rstd * g0[j] + b0[j]; r1[j] = (v[8 * k + 4 + j] - mean) * rstd * g1[j] + b1[j]; }
;       if (TO_BF16) *(uint4*)(X1 + row * 1024 + c) = pk8(r0, r1);
;       else { __builtin_nontemporal_store(r0, (f32x4*)(Y + row * 1024 + c)); __builtin_nontemporal_store(r1, (f32x4*)(Y + row * 1024 + c + 4)); }
;     }
;   }
.LBB0_930:
	s_waitcnt vmcnt(2)
	v_lshlrev_b32_e32 v40, 16, v18
	v_and_b32_e32 v41, 0xffff0000, v18
	v_lshlrev_b32_e32 v36, 16, v19
	v_and_b32_e32 v37, 0xffff0000, v19
	v_lshlrev_b32_e32 v38, 16, v20
	v_and_b32_e32 v39, 0xffff0000, v20
	v_lshlrev_b32_e32 v34, 16, v21
	v_and_b32_e32 v35, 0xffff0000, v21
	v_lshlrev_b32_e32 v48, 16, v22
	v_and_b32_e32 v49, 0xffff0000, v22
	v_lshlrev_b32_e32 v44, 16, v23
	v_and_b32_e32 v45, 0xffff0000, v23
	v_lshlrev_b32_e32 v46, 16, v24
	v_and_b32_e32 v47, 0xffff0000, v24
	v_lshlrev_b32_e32 v42, 16, v25
	v_and_b32_e32 v43, 0xffff0000, v25
	v_lshl_add_u64 v[2:3], v[2:3], 0, s[2:3]
	v_lshl_add_u64 v[70:71], v[70:71], 0, s[4:5]
	s_nop 0
	global_load_dwordx4 v[18:21], v[70:71], off nt
	global_load_dwordx4 v[22:25], v[70:71], off offset:1024 nt
	v_add_f32_e32 v26, 0, v40
	v_add_f32_e32 v26, v26, v41
	v_add_f32_e32 v26, v26, v36
	v_add_f32_e32 v26, v26, v37
	v_add_f32_e32 v26, v26, v38
	v_add_f32_e32 v26, v26, v39
	v_add_f32_e32 v26, v26, v34
	v_add_f32_e32 v26, v26, v35
	v_add_f32_e32 v26, v26, v48
	v_add_f32_e32 v26, v26, v49
	v_add_f32_e32 v26, v26, v44
	v_add_f32_e32 v26, v26, v45
	v_add_f32_e32 v26, v26, v46
	v_add_f32_e32 v26, v26, v47
	v_add_f32_e32 v26, v26, v42
	v_add_f32_e32 v26, v26, v43
	ds_bpermute_b32 v27, v11, v26
	s_waitcnt lgkmcnt(0)
	v_add_f32_e32 v26, v26, v27
	ds_bpermute_b32 v27, v12, v26
	s_waitcnt lgkmcnt(0)
	v_add_f32_e32 v26, v26, v27
	ds_bpermute_b32 v27, v13, v26
	s_waitcnt lgkmcnt(0)
	v_add_f32_e32 v26, v26, v27
	ds_bpermute_b32 v27, v14, v26
	s_waitcnt lgkmcnt(0)
	v_add_f32_e32 v26, v26, v27
	ds_bpermute_b32 v27, v15, v26
	s_waitcnt lgkmcnt(0)
	v_add_f32_e32 v26, v26, v27
	ds_bpermute_b32 v27, v16, v26
	s_waitcnt lgkmcnt(0)
	v_add_f32_e32 v26, v26, v27
	v_mul_f32_e32 v50, 0x3a800000, v26
	v_pk_add_f32 v[40:41], v[40:41], v[50:51] op_sel_hi:[1,0] neg_lo:[0,1] neg_hi:[0,1]
	v_pk_add_f32 v[36:37], v[36:37], v[50:51] op_sel_hi:[1,0] neg_lo:[0,1] neg_hi:[0,1]
	v_pk_add_f32 v[38:39], v[38:39], v[50:51] op_sel_hi:[1,0] neg_lo:[0,1] neg_hi:[0,1]
	v_pk_add_f32 v[34:35], v[34:35], v[50:51] op_sel_hi:[1,0] neg_lo:[0,1] neg_hi:[0,1]
	v_pk_add_f32 v[48:49], v[48:49], v[50:51] op_sel_hi:[1,0] neg_lo:[0,1] neg_hi:[0,1]
	v_pk_add_f32 v[44:45], v[44:45], v[50:51] op_sel_hi:[1,0] neg_lo:[0,1] neg_hi:[0,1]
	v_pk_add_f32 v[46:47], v[46:47], v[50:51] op_sel_hi:[1,0] neg_lo:[0,1] neg_hi:[0,1]
	v_pk_add_f32 v[42:43], v[42:43], v[50:51] op_sel_hi:[1,0] neg_lo:[0,1] neg_hi:[0,1]
	v_pk_mul_f32 v[50:51], v[40:41], v[40:41]
	v_pk_mul_f32 v[52:53], v[36:37], v[36:37]
	v_add_f32_e32 v50, v50, v51
	v_add_f32_e32 v50, v52, v50
	v_pk_mul_f32 v[54:55], v[38:39], v[38:39]
	v_add_f32_e32 v50, v53, v50
	v_add_f32_e32 v50, v54, v50
	v_pk_mul_f32 v[56:57], v[34:35], v[34:35]
	v_add_f32_e32 v50, v55, v50
	v_add_f32_e32 v50, v56, v50
	v_pk_mul_f32 v[58:59], v[48:49], v[48:49]
	v_add_f32_e32 v50, v57, v50
	v_add_f32_e32 v50, v58, v50
	v_pk_mul_f32 v[60:61], v[44:45], v[44:45]
	v_add_f32_e32 v50, v59, v50
	v_add_f32_e32 v50, v60, v50
	v_pk_mul_f32 v[62:63], v[46:47], v[46:47]
	v_add_f32_e32 v50, v61, v50
	v_add_f32_e32 v50, v62, v50
	v_pk_mul_f32 v[64:65], v[42:43], v[42:43]
	v_add_f32_e32 v50, v63, v50
	v_add_f32_e32 v50, v64, v50
	v_add_f32_e32 v50, v65, v50
	ds_bpermute_b32 v51, v11, v50
	s_waitcnt lgkmcnt(0)
	v_add_f32_e32 v50, v50, v51
	ds_bpermute_b32 v51, v12, v50
	s_waitcnt lgkmcnt(0)
	v_add_f32_e32 v50, v50, v51
	ds_bpermute_b32 v51, v13, v50
	s_waitcnt lgkmcnt(0)
	v_add_f32_e32 v50, v50, v51
	ds_bpermute_b32 v51, v14, v50
	s_waitcnt lgkmcnt(0)
	v_add_f32_e32 v50, v50, v51
	ds_bpermute_b32 v51, v15, v50
	s_waitcnt lgkmcnt(0)
	v_add_f32_e32 v50, v50, v51
	ds_bpermute_b32 v51, v16, v50
	s_waitcnt lgkmcnt(0)
	v_add_f32_e32 v50, v50, v51
	v_fmamk_f32 v50, v50, 0x3a800000, v17
	v_mul_f32_e32 v51, 0x4b800000, v50
	v_cmp_gt_f32_e32 vcc, s10, v50
	s_nop 1
	v_cndmask_b32_e32 v50, v50, v51, vcc
	v_rsq_f32_e32 v50, v50
	s_nop 0
	v_mul_f32_e32 v51, 0x45800000, v50
	v_cndmask_b32_e32 v50, v50, v51, vcc
	v_pk_mul_f32 v[40:41], v[40:41], v[50:51] op_sel_hi:[1,0]
	v_pk_mul_f32 v[38:39], v[38:39], v[50:51] op_sel_hi:[1,0]
	v_pk_mul_f32 v[36:37], v[36:37], v[50:51] op_sel_hi:[1,0]
	v_pk_mul_f32 v[34:35], v[34:35], v[50:51] op_sel_hi:[1,0]
	v_pk_fma_f32 v[26:27], v[74:75], v[40:41], v[82:83]
	v_pk_fma_f32 v[30:31], v[78:79], v[38:39], v[86:87]
	v_pk_fma_f32 v[28:29], v[76:77], v[36:37], v[84:85]
	v_pk_fma_f32 v[32:33], v[80:81], v[34:35], v[88:89]
	v_cvt_pk_bf16_f32 v26, v26, v27
	v_cvt_pk_bf16_f32 v27, v28, v29
	v_cvt_pk_bf16_f32 v28, v30, v31
	v_cvt_pk_bf16_f32 v29, v32, v33
	global_store_dwordx4 v[8:9], v[26:29], off
	v_pk_mul_f32 v[34:35], v[48:49], v[50:51] op_sel_hi:[1,0]
	v_pk_mul_f32 v[36:37], v[46:47], v[50:51] op_sel_hi:[1,0]
	v_pk_mul_f32 v[38:39], v[44:45], v[50:51] op_sel_hi:[1,0]
	v_pk_mul_f32 v[40:41], v[42:43], v[50:51] op_sel_hi:[1,0]
	v_cmp_lt_u64_e32 vcc, s[8:9], v[2:3]
	s_or_b64 s[6:7], vcc, s[6:7]
	v_pk_fma_f32 v[52:53], v[90:91], v[34:35], v[98:99]
	v_pk_fma_f32 v[56:57], v[94:95], v[36:37], v[102:103]
	v_pk_fma_f32 v[54:55], v[92:93], v[38:39], v[100:101]
	v_pk_fma_f32 v[58:59], v[96:97], v[40:41], v[104:105]
	v_cvt_pk_bf16_f32 v30, v52, v53
	v_cvt_pk_bf16_f32 v31, v54, v55
	v_cvt_pk_bf16_f32 v32, v56, v57
	v_cvt_pk_bf16_f32 v33, v58, v59
	global_store_dwordx4 v[8:9], v[30:33], off offset:1024
	v_lshl_add_u64 v[8:9], v[8:9], 0, s[4:5]
	s_andn2_b64 exec, exec, s[6:7]
	s_cbranch_execnz .LBB0_930
	s_waitcnt vmcnt(0)

; DI float bflo(unsigned u) { return __uint_as_float(u << 16); }
; DI float bfhi(unsigned u) { return __uint_as_float(u & 0xffff0000u); }
; template <bool TO_BF16>
; DI void phase_ln(const Params& P, const float* gam, const float* bet) {
;   const int wid = threadIdx.x >> 6, lane = threadIdx.x & 63;
;   float* Y = P.out + O_Y;
;   u16* X1 = (u16*)(P.ws + R_X1);
;   const u16* SRC = (const u16*)(P.ws + (TO_BF16 ? R_TB : R_T2B));
;   for (long row = (long)blockIdx.x * 8 + wid; row < MTOK; row += (long)gridDim.x * 8) {
;     const u16* src = SRC + row * 1024;
;     float v[16];
;     float s = 0.f;
;     for (int k = 0; k < 2; ++k) {
;       const u32x4_ u_ = __builtin_nontemporal_load((const u32x4_*)(src + k * 512 + lane * 8));
;       const uint4 u = make_uint4(u_[0], u_[1], u_[2], u_[3]);
;       v[8 * k + 0] = bflo(u.x); v[8 * k + 1] = bfhi(u.x); v[8 * k + 2] = bflo(u.y); v[8 * k + 3] = bfhi(u.y);
;       v[8 * k + 4] = bflo(u.z); v[8 * k + 5] = bfhi(u.z); v[8 * k + 6] = bflo(u.w); v[8 * k + 7] = bfhi(u.w);
;     }
;     for (int e = 0; e < 16; ++e) s += v[e];
;     for (int d = 1; d < 64; d <<= 1) s += __shfl_xor(s, d);
;     const float mean = s * (1.0f / 1024.0f);
;     float s2 = 0.f;
;     for (int e = 0; e < 16; ++e) { const float d = v[e] - mean; s2 += d * d; }
;     for (int d = 1; d < 64; d <<= 1) s2 += __shfl_xor(s2, d);
;     const float rstd = rsqrtf(s2 * (1.0f / 1024.0f) + 1e-5f);
;     for (int k = 0; k < 2; ++k) {
;       const int c = k * 512 + lane * 8;
;       f32x4 g0 = *(const f32x4*)(gam + c), g1 = *(const f32x4*)(gam + c + 4), b0 = *(const f32x4*)(bet + c), b1 = *(const f32x4*)(bet + c + 4), r0, r1;
.LBB0_995:
	s_cmp_lt_i32 s96, 9
	s_cselect_b64 s[0:1], -1, 0
	s_cmp_gt_i32 s97, 8
	s_cselect_b64 s[2:3], -1, 0
	s_and_b64 s[0:1], s[0:1], s[2:3]
	s_andn2_b64 vcc, exec, s[0:1]
	s_cbranch_vccnz .LBB0_1011
	v_readlane_b32 s0, v250, 2
	v_readlane_b32 s1, v250, 3
	s_load_dwordx8 s[4:11], s[0:1], 0x98
	s_mov_b32 s91, 0
	s_lshl_b64 s[0:1], s[90:91], 3
	v_or_b32_e32 v2, s0, v1
	v_mov_b32_e32 v3, s1
	s_mov_b64 s[0:1], 0x10100
	v_and_b32_e32 v12, 0x3ff, v0
	v_cmp_gt_u64_e32 vcc, s[0:1], v[2:3]
	s_waitcnt lgkmcnt(0)
	s_and_saveexec_b64 s[0:1], vcc
	s_cbranch_execz .LBB0_999
	v_mbcnt_lo_u32_b32 v4, -1, 0
	v_mbcnt_hi_u32_b32 v4, -1, v4
	v_and_b32_e32 v5, 64, v4
	v_add_u32_e32 v5, 64, v5
	v_xor_b32_e32 v6, 1, v4
	v_cmp_lt_i32_e32 vcc, v6, v5
	v_mov_b32_e32 v11, 0
	v_and_b32_e32 v19, 63, v12
	v_cndmask_b32_e32 v6, v4, v6, vcc
	v_lshlrev_b32_e32 v13, 2, v6
	v_xor_b32_e32 v6, 2, v4
	v_cmp_lt_i32_e32 vcc, v6, v5
	v_readlane_b32 s2, v250, 0
	v_readlane_b32 s3, v250, 1
	v_cndmask_b32_e32 v6, v4, v6, vcc
	v_lshlrev_b32_e32 v14, 2, v6
	v_xor_b32_e32 v6, 4, v4
	v_cmp_lt_i32_e32 vcc, v6, v5
	s_mov_b32 s12, s2
	s_mov_b32 s13, s91
	v_cndmask_b32_e32 v6, v4, v6, vcc
	v_lshlrev_b32_e32 v15, 2, v6
	v_xor_b32_e32 v6, 8, v4
	v_cmp_lt_i32_e32 vcc, v6, v5
	s_lshl_b64 s[2:3], s[12:13], 3
	s_nop 0
	v_cndmask_b32_e32 v6, v4, v6, vcc
	v_lshlrev_b32_e32 v16, 2, v6
	v_xor_b32_e32 v6, 16, v4
	v_cmp_lt_i32_e32 vcc, v6, v5
	s_nop 1
	v_cndmask_b32_e32 v6, v4, v6, vcc
	v_lshlrev_b32_e32 v17, 2, v6
	v_xor_b32_e32 v6, 32, v4
	v_cmp_lt_i32_e32 vcc, v6, v5
	s_nop 1
	v_cndmask_b32_e32 v4, v4, v6, vcc
	v_lshlrev_b32_e32 v18, 2, v4
	v_lshlrev_b32_e32 v4, 5, v12
	v_and_b32_e32 v10, 0x7e0, v4
	v_lshl_add_u64 v[4:5], s[4:5], 0, v[10:11]
	v_lshl_add_u64 v[6:7], s[6:7], 0, v[10:11]
	s_lshl_b64 s[4:5], s[90:91], 15
	v_lshlrev_b32_e32 v10, 12, v1
	v_lshl_add_u64 v[8:9], s[4:5], 0, v[10:11]
	s_lshl_b64 s[6:7], s[90:91], 14
	v_lshlrev_b32_e32 v10, 11, v1
	v_lshl_add_u64 v[10:11], s[6:7], 0, v[10:11]
	v_lshl_or_b32 v10, v19, 4, v10
	v_lshl_or_b32 v8, v19, 5, v8
	v_lshl_add_u64 v[10:11], s[10:11], 0, v[10:11]
	s_mov_b64 s[6:7], 0x274fb900
	v_lshl_add_u64 v[8:9], s[8:9], 0, v[8:9]
	s_lshl_b64 s[4:5], s[12:13], 15
	v_lshl_add_u64 v[10:11], v[10:11], 0, s[6:7]
	s_lshl_b64 s[6:7], s[12:13], 14
	s_mov_b64 s[8:9], 0
	v_mov_b32_e32 v1, 0x3727c5ac
	s_mov_b32 s12, 0x800000
	s_mov_b64 s[10:11], 0x100ff
	global_load_dwordx4 v[74:77], v[4:5], off
	global_load_dwordx4 v[78:81], v[4:5], off offset:16
	global_load_dwordx4 v[82:85], v[6:7], off
	global_load_dwordx4 v[86:89], v[6:7], off offset:16
	global_load_dwordx4 v[90:93], v[4:5], off offset:2048
	global_load_dwordx4 v[94:97], v[4:5], off offset:2064
	global_load_dwordx4 v[98:101], v[6:7], off offset:2048
	global_load_dwordx4 v[102:105], v[6:7], off offset:2064
	global_load_dwordx4 v[20:23], v[10:11], off nt
	global_load_dwordx4 v[24:27], v[10:11], off offset:1024 nt
	v_lshl_add_u64 v[10:11], v[10:11], 0, s[6:7]
	s_waitcnt vmcnt(0)
; DI float bflo(unsigned u) { return __uint_as_float(u << 16); }
; DI float bfhi(unsigned u) { return __uint_as_float(u & 0xffff0000u); }
; DI uint4 pk8(f32x4 a, f32x4 b) { return make_uint4(pack2(a[0], a[1]), pack2(a[2], a[3]), pack2(b[0], b[1]), pack2(b[2], b[3])); }
; template <bool TO_BF16>
; DI void phase_ln(const Params& P, const float* gam, const float* bet) {
;     ...
;   for (long row = (long)blockIdx.x * 8 + wid; row < MTOK; row += (long)gridDim.x * 8) {
;     const u16* src = SRC + row * 1024;
;     float v[16];
;     float s = 0.f;
;     for (int k = 0; k < 2; ++k) {
;       const u32x4_ u_ = __builtin_nontemporal_load((const u32x4_*)(src + k * 512 + lane * 8));
;       const uint4 u = make_uint4(u_[0], u_[1], u_[2], u_[3]);
;       v[8 * k + 0] = bflo(u.x); v[8 * k + 1] = bfhi(u.x); v[8 * k + 2] = bflo(u.y); v[8 * k + 3] = bfhi(u.y);
;       v[8 * k + 4] = bflo(u.z); v[8 * k + 5] = bfhi(u.z); v[8 * k + 6] = bflo(u.w); v[8 * k + 7] = bfhi(u.w);
;     }
;     for (int e = 0; e < 16; ++e) s += v[e];
;     for (int d = 1; d < 64; d <<= 1) s += __shfl_xor(s, d);
;     const float mean = s * (1.0f / 1024.0f);
;     float s2 = 0.f;
;     for (int e = 0; e < 16; ++e) { const float d = v[e] - mean; s2 += d * d; }
;     for (int d = 1; d < 64; d <<= 1) s2 += __shfl_xor(s2, d);
;     const float rstd = rsqrtf(s2 * (1.0f / 1024.0f) + 1e-5f);
;     for (int k = 0; k < 2; ++k) {
;       const int c = k * 512 + lane * 8;
;       f32x4 g0 = *(const f32x4*)(gam + c), g1 = *(const f32x4*)(gam + c + 4), b0 = *(const f32x4*)(bet + c), b1 = *(const f32x4*)(bet + c + 4), r0, r1;
;       for (int j = 0; j < 4; ++j) { r0[j] = (v[8 * k + j] - mean) * rstd * g0[j] + b0[j]; r1[j] = (v[8 * k + 4 + j] - mean) * rstd * g1[j] + b1[j]; }
;       if (TO_BF16) *(uint4*)(X1 + row * 1024 + c) = pk8(r0, r1);
;       else { __builtin_nontemporal_store(r0, (f32x4*)(Y + row * 1024 + c)); __builtin_nontemporal_store(r1, (f32x4*)(Y + row * 1024 + c + 4)); }
;     }
;   }
.LBB0_998:
	s_waitcnt vmcnt(4)
	v_lshlrev_b32_e32 v46, 16, v20
	v_and_b32_e32 v47, 0xffff0000, v20
	v_lshlrev_b32_e32 v28, 16, v21
	v_and_b32_e32 v29, 0xffff0000, v21
	v_lshlrev_b32_e32 v44, 16, v22
	v_and_b32_e32 v45, 0xffff0000, v22
	v_lshlrev_b32_e32 v30, 16, v23
	v_and_b32_e32 v31, 0xffff0000, v23
	v_lshlrev_b32_e32 v50, 16, v24
	v_and_b32_e32 v51, 0xffff0000, v24
	v_lshlrev_b32_e32 v32, 16, v25
	v_and_b32_e32 v33, 0xffff0000, v25
	v_lshlrev_b32_e32 v48, 16, v26
	v_and_b32_e32 v49, 0xffff0000, v26
	v_lshlrev_b32_e32 v34, 16, v27
	v_and_b32_e32 v35, 0xffff0000, v27
	v_lshl_add_u64 v[2:3], v[2:3], 0, s[2:3]
	global_load_dwordx4 v[20:23], v[10:11], off nt
	global_load_dwordx4 v[24:27], v[10:11], off offset:1024 nt
	v_lshl_add_u64 v[10:11], v[10:11], 0, s[6:7]
	v_add_f32_e32 v19, 0, v46
	v_add_f32_e32 v19, v19, v47
	v_add_f32_e32 v19, v19, v28
	v_add_f32_e32 v19, v19, v29
	v_add_f32_e32 v19, v19, v44
	v_add_f32_e32 v19, v19, v45
	v_add_f32_e32 v19, v19, v30
	v_add_f32_e32 v19, v19, v31
	v_add_f32_e32 v19, v19, v50
	v_add_f32_e32 v19, v19, v51
	v_add_f32_e32 v19, v19, v32
	v_add_f32_e32 v19, v19, v33
	v_add_f32_e32 v19, v19, v48
	v_add_f32_e32 v19, v19, v49
	v_add_f32_e32 v19, v19, v34
	v_add_f32_e32 v19, v19, v35
	ds_bpermute_b32 v52, v13, v19
	s_waitcnt lgkmcnt(0)
	v_add_f32_e32 v19, v19, v52
	ds_bpermute_b32 v52, v14, v19
	s_waitcnt lgkmcnt(0)
	v_add_f32_e32 v19, v19, v52
	ds_bpermute_b32 v52, v15, v19
	s_waitcnt lgkmcnt(0)
	v_add_f32_e32 v19, v19, v52
	ds_bpermute_b32 v52, v16, v19
	s_waitcnt lgkmcnt(0)
	v_add_f32_e32 v19, v19, v52
	ds_bpermute_b32 v52, v17, v19
	s_waitcnt lgkmcnt(0)
	v_add_f32_e32 v19, v19, v52
	ds_bpermute_b32 v52, v18, v19
	s_waitcnt lgkmcnt(0)
	v_add_f32_e32 v19, v19, v52
	v_mul_f32_e32 v52, 0x3a800000, v19
	v_pk_add_f32 v[46:47], v[46:47], v[52:53] op_sel_hi:[1,0] neg_lo:[0,1] neg_hi:[0,1]
	v_pk_add_f32 v[28:29], v[28:29], v[52:53] op_sel_hi:[1,0] neg_lo:[0,1] neg_hi:[0,1]
	v_pk_add_f32 v[44:45], v[44:45], v[52:53] op_sel_hi:[1,0] neg_lo:[0,1] neg_hi:[0,1]
	v_pk_add_f32 v[30:31], v[30:31], v[52:53] op_sel_hi:[1,0] neg_lo:[0,1] neg_hi:[0,1]
	v_pk_add_f32 v[50:51], v[50:51], v[52:53] op_sel_hi:[1,0] neg_lo:[0,1] neg_hi:[0,1]
	v_pk_add_f32 v[32:33], v[32:33], v[52:53] op_sel_hi:[1,0] neg_lo:[0,1] neg_hi:[0,1]
	v_pk_add_f32 v[48:49], v[48:49], v[52:53] op_sel_hi:[1,0] neg_lo:[0,1] neg_hi:[0,1]
	v_pk_add_f32 v[34:35], v[34:35], v[52:53] op_sel_hi:[1,0] neg_lo:[0,1] neg_hi:[0,1]
	v_pk_mul_f32 v[56:57], v[46:47], v[46:47]
	v_pk_mul_f32 v[58:59], v[28:29], v[28:29]
	v_pk_mul_f32 v[60:61], v[44:45], v[44:45]
	v_pk_mul_f32 v[62:63], v[30:31], v[30:31]
	v_pk_mul_f32 v[64:65], v[50:51], v[50:51]
	v_pk_mul_f32 v[66:67], v[32:33], v[32:33]
	v_pk_mul_f32 v[68:69], v[48:49], v[48:49]
	v_pk_mul_f32 v[70:71], v[34:35], v[34:35]
	v_add_f32_e32 v19, v56, v57
	v_add_f32_e32 v19, v58, v19
	v_add_f32_e32 v19, v59, v19
	v_add_f32_e32 v19, v60, v19
	v_add_f32_e32 v19, v61, v19
	v_add_f32_e32 v19, v62, v19
	v_add_f32_e32 v19, v63, v19
	v_add_f32_e32 v19, v64, v19
	v_add_f32_e32 v19, v65, v19
	v_add_f32_e32 v19, v66, v19
	v_add_f32_e32 v19, v67, v19
	v_add_f32_e32 v19, v68, v19
	v_add_f32_e32 v19, v69, v19
	v_add_f32_e32 v19, v70, v19
	v_add_f32_e32 v19, v71, v19
	ds_bpermute_b32 v52, v13, v19
	s_waitcnt lgkmcnt(0)
	v_add_f32_e32 v19, v19, v52
	ds_bpermute_b32 v52, v14, v19
	s_waitcnt lgkmcnt(0)
	v_add_f32_e32 v19, v19, v52
	ds_bpermute_b32 v52, v15, v19
	s_waitcnt lgkmcnt(0)
	v_add_f32_e32 v19, v19, v52
	ds_bpermute_b32 v52, v16, v19
	s_waitcnt lgkmcnt(0)
	v_add_f32_e32 v19, v19, v52
	ds_bpermute_b32 v52, v17, v19
	s_waitcnt lgkmcnt(0)
	v_add_f32_e32 v19, v19, v52
	ds_bpermute_b32 v52, v18, v19
	s_waitcnt lgkmcnt(0)
	v_add_f32_e32 v19, v19, v52
	v_fmamk_f32 v19, v19, 0x3a800000, v1
	v_mul_f32_e32 v52, 0x4b800000, v19
	v_cmp_gt_f32_e32 vcc, s12, v19
	s_nop 1
	v_cndmask_b32_e32 v19, v19, v52, vcc
	v_rsq_f32_e32 v19, v19
	s_nop 0
	v_mul_f32_e32 v52, 0x45800000, v19
	v_cndmask_b32_e32 v56, v19, v52, vcc
	v_pk_mul_f32 v[46:47], v[46:47], v[56:57] op_sel_hi:[1,0]
	v_pk_mul_f32 v[28:29], v[28:29], v[56:57] op_sel_hi:[1,0]
	v_pk_mul_f32 v[44:45], v[44:45], v[56:57] op_sel_hi:[1,0]
	v_pk_mul_f32 v[30:31], v[30:31], v[56:57] op_sel_hi:[1,0]
	v_pk_mul_f32 v[50:51], v[50:51], v[56:57] op_sel_hi:[1,0]
	v_pk_mul_f32 v[32:33], v[32:33], v[56:57] op_sel_hi:[1,0]
	v_pk_mul_f32 v[48:49], v[48:49], v[56:57] op_sel_hi:[1,0]
	v_pk_mul_f32 v[34:35], v[34:35], v[56:57] op_sel_hi:[1,0]
	v_pk_fma_f32 v[36:37], v[74:75], v[46:47], v[82:83]
	v_pk_fma_f32 v[38:39], v[76:77], v[28:29], v[84:85]
	v_pk_fma_f32 v[40:41], v[78:79], v[44:45], v[86:87]
	v_pk_fma_f32 v[42:43], v[80:81], v[30:31], v[88:89]
	global_store_dwordx4 v[8:9], v[36:39], off nt
	global_store_dwordx4 v[8:9], v[40:43], off offset:16 nt
	v_cmp_lt_u64_e32 vcc, s[10:11], v[2:3]
	s_or_b64 s[8:9], vcc, s[8:9]
	v_pk_fma_f32 v[58:59], v[90:91], v[50:51], v[98:99]
	v_pk_fma_f32 v[60:61], v[92:93], v[32:33], v[100:101]
	v_pk_fma_f32 v[62:63], v[94:95], v[48:49], v[102:103]
	v_pk_fma_f32 v[64:65], v[96:97], v[34:35], v[104:105]
	global_store_dwordx4 v[8:9], v[58:61], off offset:2048 nt
	global_store_dwordx4 v[8:9], v[62:65], off offset:2064 nt
	v_lshl_add_u64 v[8:9], v[8:9], 0, s[4:5]
	s_andn2_b64 exec, exec, s[8:9]
	s_cbranch_execnz .LBB0_998
	s_waitcnt vmcnt(0)
